# P2b: norm-weight chunks hoisted out of the token loop, ckv row loads issued with the cq row loads (1 round trip per token instead of 5)
# speedup vs baseline: 1.0202x; 1.0009x over previous
.LBB0_584:
	s_or_b64 exec, exec, s[0:1]
	v_mov_b32_e32 v2, v250
	s_waitcnt lgkmcnt(0)
	s_barrier
	v_readlane_b32 s0, v254, 42
	v_ashrrev_i32_e32 v0, 6, v2
	s_add_u32 s40, s50, 0x131ed700
	v_add_u32_e32 v9, s0, v0
	s_movk_i32 s0, 0x2200
	s_addc_u32 s41, s51, 0
	v_cmp_gt_i32_e32 vcc, s0, v9
	v_readlane_b32 s1, v254, 43
	s_and_saveexec_b64 s[4:5], vcc
	s_mov_b32 s34, s84
	s_cbranch_execz .LBB0_595
	v_lshlrev_b32_e32 v1, 2, v2
	v_and_b32_e32 v8, 0xfc, v1
	v_mbcnt_lo_u32_b32 v1, -1, 0
	v_mbcnt_hi_u32_b32 v1, -1, v1
	v_and_b32_e32 v3, 64, v1
	v_add_u32_e32 v3, 64, v3
	v_xor_b32_e32 v4, 32, v1
	v_cmp_lt_i32_e32 vcc, v4, v3
	v_readlane_b32 s0, v254, 42
	s_add_u32 s6, s48, 0x9a3c000
	v_cndmask_b32_e32 v4, v1, v4, vcc
	v_lshlrev_b32_e32 v30, 2, v4
	v_xor_b32_e32 v4, 16, v1
	v_cmp_lt_i32_e32 vcc, v4, v3
	v_readlane_b32 s80, v254, 18
	v_readlane_b32 s1, v254, 43
	v_cndmask_b32_e32 v4, v1, v4, vcc
	v_lshlrev_b32_e32 v31, 2, v4
	v_xor_b32_e32 v4, 8, v1
	v_cmp_lt_i32_e32 vcc, v4, v3
	s_addc_u32 s7, s49, 0
	v_readlane_b32 s81, v254, 19
	v_cndmask_b32_e32 v4, v1, v4, vcc
	v_lshlrev_b32_e32 v32, 2, v4
	v_xor_b32_e32 v4, 4, v1
	v_cmp_lt_i32_e32 vcc, v4, v3
	v_readlane_b32 s82, v254, 20
	v_readlane_b32 s83, v254, 21
	v_cndmask_b32_e32 v4, v1, v4, vcc
	v_lshlrev_b32_e32 v33, 2, v4
	v_xor_b32_e32 v4, 2, v1
	v_cmp_lt_i32_e32 vcc, v4, v3
	v_readlane_b32 s84, v254, 22
	v_readlane_b32 s85, v254, 23
	v_cndmask_b32_e32 v4, v1, v4, vcc
	v_lshlrev_b32_e32 v34, 2, v4
	v_xor_b32_e32 v4, 1, v1
	v_cmp_lt_i32_e32 vcc, v4, v3
	v_readlane_b32 s86, v254, 24
	v_readlane_b32 s87, v254, 25
	v_cndmask_b32_e32 v1, v1, v4, vcc
	v_readlane_b32 s88, v254, 26
	v_readlane_b32 s89, v254, 27
	v_readlane_b32 s90, v254, 28
	v_readlane_b32 s91, v254, 29
	v_readlane_b32 s92, v254, 30
	v_readlane_b32 s93, v254, 31
	v_readlane_b32 s94, v254, 32
	v_readlane_b32 s95, v254, 33
	s_mov_b32 s2, s0
	s_ashr_i32 s3, s0, 31
	v_writelane_b32 v254, s0, 42
	v_lshlrev_b32_e32 v35, 2, v1
	v_ashrrev_i32_e32 v1, 31, v0
	v_writelane_b32 v254, s1, 43
	v_lshl_add_u64 v[0:1], v[0:1], 0, s[2:3]
	v_readlane_b32 s0, v254, 40
	v_readlane_b32 s1, v254, 41
	v_lshlrev_b64 v[18:19], 11, v[0:1]
	v_lshlrev_b64 v[16:17], 10, v[0:1]
	s_mov_b32 s2, s0
	s_ashr_i32 s3, s0, 31
	v_lshl_add_u64 v[0:1], s[48:49], 0, v[18:19]
	s_mov_b64 s[0:1], 0x8400000
	v_lshl_add_u64 v[20:21], v[0:1], 0, s[0:1]
	s_mov_b32 s0, s2
	v_mov_b32_e32 v11, 0
	v_lshlrev_b32_e32 v10, 2, v8
	v_and_b32_e32 v2, 63, v2
	v_writelane_b32 v254, s0, 40
	s_mov_b32 s84, s34
	v_lshl_add_u64 v[12:13], s[86:87], 0, v[10:11]
	v_lshl_add_u64 v[14:15], s[36:37], 0, v[10:11]
	v_lshl_or_b32 v16, v2, 3, v16
	s_lshl_b64 s[8:9], s[2:3], 10
	v_writelane_b32 v254, s1, 41
	s_lshl_b64 s[10:11], s[2:3], 11
	v_lshl_or_b32 v18, v2, 4, v18
	s_mov_b64 s[12:13], 0
	v_mov_b32_e32 v36, 0x358637bd
	s_mov_b32 s2, 0x800000
	s_mov_b32 s3, 0xe25d000
	s_mov_b32 s14, 0xaf5d000
	s_movk_i32 s15, 0x1fff
	s_movk_i32 s22, 0x1040
	s_mov_b64 s[18:19], 0x1000
	s_movk_i32 s23, 0x480
	s_movk_i32 s24, 0x21ff
	global_load_dwordx4 v[46:49], v[12:13], off
	global_load_dwordx4 v[50:53], v[12:13], off offset:1024
	global_load_dwordx4 v[54:57], v[14:15], off
	global_load_dwordx4 v[58:61], v[14:15], off offset:1024
	s_branch .LBB0_587

.LBB0_587:
	v_lshl_add_u64 v[28:29], s[50:51], 0, v[18:19]
	v_add_co_u32_e32 v4, vcc, 0x9e5d000, v28
	s_nop 1
	v_addc_co_u32_e32 v5, vcc, 0, v29, vcc
	global_load_dwordx4 v[0:3], v[4:5], off offset:1792
	s_nop 0
	global_load_dwordx4 v[4:7], v[4:5], off offset:2816
	s_nop 0
	v_add_co_u32_e32 v70, vcc, s14, v28
	s_nop 1
	v_addc_co_u32_e32 v71, vcc, 0, v29, vcc
	global_load_dwordx4 v[62:65], v[70:71], off offset:1792
	global_load_dwordx4 v[66:69], v[70:71], off offset:2816
	s_waitcnt vmcnt(3)
	v_mov_b32_e32 v38, v1
	s_waitcnt vmcnt(2)
	v_mov_b32_e32 v39, v5
	v_mov_b32_e32 v22, v0
	v_mov_b32_e32 v23, v4
	v_pk_mul_f32 v[38:39], v[38:39], v[38:39]
	v_mov_b32_e32 v40, v2
	v_mov_b32_e32 v41, v6
	v_pk_fma_f32 v[22:23], v[22:23], v[22:23], v[38:39]
	v_mov_b32_e32 v42, v3
	v_mov_b32_e32 v43, v7
	v_pk_fma_f32 v[22:23], v[40:41], v[40:41], v[22:23]
	s_nop 0
	v_pk_fma_f32 v[22:23], v[42:43], v[42:43], v[22:23]
	s_nop 0
	v_add_f32_e32 v10, v22, v23
	ds_bpermute_b32 v22, v30, v10
	s_waitcnt lgkmcnt(0)
	v_add_f32_e32 v10, v10, v22
	ds_bpermute_b32 v22, v31, v10
	s_waitcnt lgkmcnt(0)
	v_add_f32_e32 v10, v10, v22
	ds_bpermute_b32 v22, v32, v10
	s_waitcnt lgkmcnt(0)
	v_add_f32_e32 v10, v10, v22
	ds_bpermute_b32 v22, v33, v10
	s_waitcnt lgkmcnt(0)
	v_add_f32_e32 v10, v10, v22
	ds_bpermute_b32 v22, v34, v10
	s_waitcnt lgkmcnt(0)
	v_add_f32_e32 v10, v10, v22
	ds_bpermute_b32 v37, v35, v10
	v_lshl_add_u64 v[22:23], s[50:51], 0, v[16:17]
	v_add_co_u32_e64 v38, s[0:1], s3, v22
	s_waitcnt lgkmcnt(0)
	v_add_f32_e32 v10, v10, v37
	v_fmamk_f32 v10, v10, 0x3b000000, v36
	v_mul_f32_e32 v37, 0x4b800000, v10
	v_cmp_gt_f32_e32 vcc, s2, v10
	v_addc_co_u32_e64 v39, s[0:1], 0, v23, s[0:1]
	s_nop 0
	v_cndmask_b32_e32 v10, v10, v37, vcc
	v_rsq_f32_e32 v10, v10
	s_nop 0
	v_mul_f32_e32 v37, 0x45800000, v10
	v_cndmask_b32_e32 v10, v10, v37, vcc
	v_pk_mul_f32 v[0:1], v[10:11], v[0:1] op_sel_hi:[0,1]
	v_pk_mul_f32 v[2:3], v[10:11], v[2:3] op_sel_hi:[0,1]
	v_pk_mul_f32 v[2:3], v[2:3], v[48:49]
	v_pk_mul_f32 v[0:1], v[0:1], v[46:47]
	v_pk_mul_f32 v[4:5], v[10:11], v[4:5] op_sel_hi:[0,1]
	v_cvt_pk_bf16_f32 v0, v0, v1
	v_cvt_pk_bf16_f32 v1, v2, v3
	global_store_dwordx2 v[38:39], v[0:1], off offset:1792
	v_pk_mul_f32 v[6:7], v[10:11], v[6:7] op_sel_hi:[0,1]
	v_add_co_u32_e32 v24, vcc, s14, v28
	v_pk_mul_f32 v[2:3], v[6:7], v[52:53]
	v_pk_mul_f32 v[0:1], v[4:5], v[50:51]
	v_addc_co_u32_e32 v25, vcc, 0, v29, vcc
	v_cvt_pk_bf16_f32 v0, v0, v1
	v_cvt_pk_bf16_f32 v1, v2, v3
	global_store_dwordx2 v[38:39], v[0:1], off offset:2304
	s_waitcnt vmcnt(2)
	v_mov_b32_e32 v4, v62
	v_mov_b32_e32 v5, v63
	v_mov_b32_e32 v6, v64
	v_mov_b32_e32 v7, v65
	v_mov_b32_e32 v0, v66
	v_mov_b32_e32 v1, v67
	v_mov_b32_e32 v2, v68
	v_mov_b32_e32 v3, v69
	v_cmp_lt_i32_e32 vcc, s15, v9
	v_mov_b32_e32 v26, v5
	v_mov_b32_e32 v27, v1
	v_mov_b32_e32 v24, v4
	v_mov_b32_e32 v25, v0
	v_pk_mul_f32 v[26:27], v[26:27], v[26:27]
	v_mov_b32_e32 v28, v6
	v_mov_b32_e32 v29, v2
	v_pk_fma_f32 v[24:25], v[24:25], v[24:25], v[26:27]
	v_mov_b32_e32 v38, v7
	v_pk_fma_f32 v[24:25], v[28:29], v[28:29], v[24:25]
	v_mov_b32_e32 v39, v3
	v_pk_fma_f32 v[24:25], v[38:39], v[38:39], v[24:25]
	s_nop 0
	v_add_f32_e32 v10, v24, v25
	ds_bpermute_b32 v24, v30, v10
	s_waitcnt lgkmcnt(0)
	v_add_f32_e32 v10, v10, v24
	ds_bpermute_b32 v24, v31, v10
	s_waitcnt lgkmcnt(0)
	v_add_f32_e32 v10, v10, v24
	ds_bpermute_b32 v24, v32, v10
	s_waitcnt lgkmcnt(0)
	v_add_f32_e32 v10, v10, v24
	ds_bpermute_b32 v24, v33, v10
	s_waitcnt lgkmcnt(0)
	v_add_f32_e32 v10, v10, v24
	ds_bpermute_b32 v24, v34, v10
	s_waitcnt lgkmcnt(0)
	v_add_f32_e32 v26, v10, v24
	ds_bpermute_b32 v27, v35, v26
	v_add_u32_e32 v10, 0xffffe000, v9
	s_and_saveexec_b64 s[0:1], vcc
	s_xor_b64 s[0:1], exec, s[0:1]
	v_add_u32_e32 v10, 0xffffe000, v9
	v_lshlrev_b64 v[24:25], 11, v[10:11]
	v_lshl_add_u64 v[24:25], s[6:7], 0, v[24:25]
	s_andn2_saveexec_b64 s[0:1], s[0:1]
	v_mov_b64_e32 v[24:25], v[20:21]
	s_or_b64 exec, exec, s[0:1]
	s_waitcnt lgkmcnt(0)
	v_add_f32_e32 v26, v26, v27
	v_add_co_u32_e32 v42, vcc, 0xeadd000, v22
	v_lshrrev_b32_e32 v27, 5, v10
	v_lshlrev_b32_e32 v10, 2, v8
	v_fmamk_f32 v37, v26, 0x3b000000, v36
	v_addc_co_u32_e32 v43, vcc, 0, v23, vcc
	v_mad_u64_u32 v[44:45], s[20:21], v27, s22, 0
	v_lshl_add_u64 v[26:27], v[24:25], 0, v[10:11]
	v_mul_f32_e32 v10, 0x4b800000, v37
	v_cmp_gt_f32_e32 vcc, s2, v37
	v_and_or_b32 v44, v9, 31, v44
	v_mov_b64_e32 v[28:29], s[40:41]
	v_cndmask_b32_e32 v10, v37, v10, vcc
	v_rsq_f32_e32 v10, v10
	v_lshl_add_u64 v[44:45], v[44:45], 0, s[18:19]
	v_mad_u64_u32 v[24:25], s[20:21], v44, s23, v[28:29]
	v_mul_f32_e32 v28, 0x45800000, v10
	v_cndmask_b32_e32 v28, v10, v28, vcc
	v_pk_mul_f32 v[4:5], v[28:29], v[4:5] op_sel_hi:[0,1]
	v_pk_mul_f32 v[6:7], v[28:29], v[6:7] op_sel_hi:[0,1]
	v_cmp_lt_i32_e64 s[0:1], s15, v9
	v_mad_u32_u24 v25, v45, s23, v25
	v_lshlrev_b32_e32 v10, 1, v8
	v_pk_mul_f32 v[6:7], v[6:7], v[56:57]
	v_pk_mul_f32 v[4:5], v[4:5], v[54:55]
	global_store_dwordx4 v[26:27], v[4:7], off
	s_nop 1
	v_cvt_pk_bf16_f32 v4, v4, v5
	v_cvt_pk_bf16_f32 v5, v6, v7
	global_store_dwordx2 v[42:43], v[4:5], off offset:1792
	s_and_saveexec_b64 s[20:21], s[0:1]
	s_cbranch_execz .LBB0_593
	v_lshl_add_u64 v[6:7], v[24:25], 0, v[10:11]
	global_store_dwordx2 v[6:7], v[4:5], off
.LBB0_593:
	s_or_b64 exec, exec, s[20:21]
	v_mov_b32_e32 v29, v28
	v_mov_b32_e32 v38, v28
	v_mov_b32_e32 v39, v28
	v_pk_mul_f32 v[2:3], v[38:39], v[2:3]
	v_pk_mul_f32 v[0:1], v[28:29], v[0:1]
	v_add_co_u32_e32 v22, vcc, 0xeadd000, v22
	v_pk_mul_f32 v[2:3], v[2:3], v[60:61]
	v_pk_mul_f32 v[0:1], v[0:1], v[58:59]
	global_store_dwordx4 v[26:27], v[0:3], off offset:1024
	v_addc_co_u32_e32 v23, vcc, 0, v23, vcc
	s_nop 0
	v_cvt_pk_bf16_f32 v0, v0, v1
	v_cvt_pk_bf16_f32 v1, v2, v3
	global_store_dwordx2 v[22:23], v[0:1], off offset:2304
	s_and_saveexec_b64 s[20:21], s[0:1]
	s_cbranch_execz .LBB0_586
	v_lshl_add_u64 v[2:3], v[24:25], 0, v[10:11]
	global_store_dwordx2 v[2:3], v[0:1], off offset:512
	s_branch .LBB0_586
